# v33 + NSA window loop: wave-uniform first-tile test taken from the scalar mask directly (cndmask/cmp_ne ballot pair removed)
# baseline (speedup 1.0000x reference)
.LBB0_965:
	v_add_u32_e32 v10, s50, v188
	v_add3_u32 v114, v10, v181, v180
	v_add_u32_e32 v115, v10, v182
	ds_read_b64_tr_b16 v[6:7], v114 offset:8192
	ds_read_b64_tr_b16 v[8:9], v114 offset:9216
	ds_read_b64_tr_b16 v[10:11], v115 offset:8192
	ds_read_b64_tr_b16 v[12:13], v115 offset:9216
	s_nop 2
	v_max_f32_e32 v2, v97, v97
	v_max_f32_e32 v3, v96, v96
	v_max_f32_e32 v2, v3, v2
	v_max3_f32 v3, v98, v99, v81
	v_max3_f32 v2, v2, v80, v82
	v_max3_f32 v2, v2, v83, v100
	v_max3_f32 v3, v3, v102, v103
	v_max3_f32 v2, v2, v101, v84
	v_max3_f32 v3, v3, v86, v87
	v_max3_f32 v2, v2, v85, v104
	v_max3_f32 v3, v3, v106, v107
	v_max3_f32 v2, v2, v105, v88
	v_max3_f32 v3, v3, v90, v91
	v_max3_f32 v2, v2, v89, v108
	v_max3_f32 v3, v3, v110, v111
	v_max3_f32 v2, v2, v109, v92
	v_max3_f32 v3, v3, v94, v95
	v_max3_f32 v2, v2, v93, v3
	v_mov_b32_e32 v3, v2
	s_nop 1
	v_permlane32_swap_b32_e32 v2, v3
	s_xor_b64 s[6:7], s[62:63], -1
	v_max_f32_e32 v3, v3, v3
	v_max_f32_e32 v2, v2, v2
	v_max_f32_e32 v2, v2, v3
	s_and_b64 s[4:5], s[62:63], exec
	s_andn2_b64 vcc, exec, s[6:7]
	s_mov_b64 s[6:7], -1
	s_cbranch_vccnz .LBB0_968
	v_cmp_lt_f32_e32 vcc, s91, v2
	s_cbranch_vccz .LBB0_974
	s_nop 0
	v_cndmask_b32_e32 v2, 0, v2, vcc
